# v45 + P5: epilogues of the two wave halves staggered (ALIGN_EPI barrier only at the last unit, no re-stagger barrier at unit transitions)
# speedup vs baseline: 1.0260x; 1.0097x over previous
.Lpeel_done_3:
	v_readlane_b32 s44, v254, 27
	v_readlane_b32 s45, v254, 28
	s_and_b64 s[44:45], s[44:45], s[10:11]
	s_and_b64 vcc, exec, s[44:45]
	s_cbranch_vccz .LBB0_2297
	s_barrier
	s_cmp_lt_i32 s16, 0
	s_mov_b64 s[44:45], -1
	s_cbranch_scc1 .LBB0_2298

.LBB0_2300:
	v_readlane_b32 s10, v254, 58
	v_readlane_b32 s11, v254, 59
	s_and_b64 vcc, exec, s[10:11]
	s_cbranch_vccnz .LBB0_2270
	s_nop 0
	s_branch .LBB0_2270
